# grid barrier: XCD leader releases its local workgroups before its own cache invalidate (6 of 7 barrier copies)
# baseline (speedup 1.0000x reference)
.LBB0_265:
	s_or_b64 exec, exec, s[24:25]
	s_mov_b64 s[24:25], exec
	v_mbcnt_lo_u32_b32 v0, s24, 0
	v_mbcnt_hi_u32_b32 v0, s25, v0
	v_cmp_eq_u32_e32 vcc, 0, v0
	s_waitcnt vmcnt(0)
	s_and_saveexec_b64 s[26:27], vcc
	s_cbranch_execz .LBB0_267
	s_bcnt1_i32_b64 s6, s[24:25]
	v_readlane_b32 s24, v254, 17
	v_mov_b32_e32 v0, s6
	v_readlane_b32 s25, v254, 18
	s_nop 4
	global_atomic_add v145, v0, s[24:25]
.LBB0_267:
	s_or_b64 exec, exec, s[26:27]
	buffer_inv sc1
	s_waitcnt vmcnt(0)

.LBB0_323:
	s_or_b64 exec, exec, s[20:21]
	s_mov_b64 s[20:21], exec
	v_mbcnt_lo_u32_b32 v0, s20, 0
	v_mbcnt_hi_u32_b32 v0, s21, v0
	v_cmp_eq_u32_e32 vcc, 0, v0
	s_waitcnt vmcnt(0)
	s_and_saveexec_b64 s[24:25], vcc
	s_cbranch_execz .LBB0_325
	s_bcnt1_i32_b64 s6, s[20:21]
	v_readlane_b32 s20, v254, 17
	v_mov_b32_e32 v0, s6
	v_readlane_b32 s21, v254, 18
	s_nop 4
	global_atomic_add v145, v0, s[20:21]
.LBB0_325:
	s_or_b64 exec, exec, s[24:25]
	buffer_inv sc1
	s_waitcnt vmcnt(0)

.LBB0_496:
	s_or_b64 exec, exec, s[8:9]
	s_mov_b64 s[8:9], exec
	v_mbcnt_lo_u32_b32 v0, s8, 0
	v_mbcnt_hi_u32_b32 v0, s9, v0
	v_cmp_eq_u32_e32 vcc, 0, v0
	s_waitcnt vmcnt(0)
	s_and_saveexec_b64 s[20:21], vcc
	s_cbranch_execz .LBB0_498
	s_bcnt1_i32_b64 s6, s[8:9]
	v_readlane_b32 s8, v254, 17
	v_mov_b32_e32 v0, s6
	v_readlane_b32 s9, v254, 18
	s_nop 4
	global_atomic_add v145, v0, s[8:9]
.LBB0_498:
	s_or_b64 exec, exec, s[20:21]
	buffer_inv sc1
	s_waitcnt vmcnt(0)
